# plus: FFN-up GEMM static unit order changed so the 88 sample-row units are spread over 88 workgroups (they were 3 per workgroup on XCD 7)
# speedup vs baseline: 1.0739x; 1.0092x over previous
.LBB0_2018:
	v_readlane_b32 s0, v252, 22
	v_readlane_b32 s1, v252, 23
	s_cmp_lt_i32 s0, 9
	s_cselect_b64 s[8:9], -1, 0
	s_cmp_gt_i32 s1, 8
	s_cselect_b64 s[0:1], -1, 0
	s_and_b64 s[0:1], s[8:9], s[0:1]
	s_andn2_b64 vcc, exec, s[0:1]
	v_writelane_b32 v254, s76, 37
	s_cbranch_vccnz .LBB0_2297
	s_load_dword s2, s[78:79], 0x2b0
	v_readfirstlane_b32 s10, v248
	s_waitcnt lgkmcnt(0)
	v_cvt_f32_u32_e32 v1, s2
	s_sub_i32 s0, 0, s2
	v_writelane_b32 v254, s2, 38
	v_rcp_iflag_f32_e32 v1, v1
	s_nop 0
	v_mul_f32_e32 v1, 0x4f7ffffe, v1
	v_cvt_u32_f32_e32 v1, v1
	s_nop 0
	v_readfirstlane_b32 s1, v1
	s_mul_i32 s0, s0, s1
	s_mul_hi_u32 s0, s1, s0
	s_add_i32 s1, s1, s0
	s_mul_hi_u32 s0, s76, s1
	s_mul_i32 s0, s0, s2
	s_sub_i32 s0, s76, s0
	s_sub_i32 s1, s0, s2
	s_cmp_ge_u32 s0, s2
	s_cselect_b32 s0, s1, s0
	s_sub_i32 s1, s0, s2
	s_cmp_ge_u32 s0, s2
	s_cselect_b32 s0, s1, s0
	s_cmpk_lt_i32 s0, 0x5d8
	s_cselect_b64 s[2:3], -1, 0
	v_writelane_b32 v254, s0, 40
	s_cmpk_gt_i32 s0, 0x5d7
	s_cbranch_scc1 .LBB0_2021
	v_readlane_b32 s4, v254, 40
	s_and_b32 s12, s4, 7
	s_lshr_b32 s14, s4, 3
	s_and_b32 s0, s14, 7
	s_lshl_b32 s12, s12, 3
	s_add_u32 s12, s12, s0
	s_lshr_b32 s14, s14, 3
	s_sub_u32 s0, s4, 0x580
	s_and_b32 s1, s0, 3
	s_add_u32 s1, s1, 64
	s_lshr_b32 s0, s0, 2
	s_cmp_lt_u32 s4, 0x580
	s_cselect_b32 s12, s12, s1
	s_cselect_b32 s14, s14, s0

.LBB0_2027:
	s_add_i32 s7, s7, 1
	v_readlane_b32 s1, v254, 56
	s_mul_i32 s10, s7, s1
	v_readlane_b32 s1, v254, 38
	s_mul_hi_u32 s11, s7, s1
	s_add_i32 s11, s11, s10
	s_mul_i32 s10, s7, s1
	v_readlane_b32 s1, v254, 40
	s_add_u32 s20, s10, s1
	v_readlane_b32 s1, v254, 58
	s_addc_u32 s21, s11, s1
	v_writelane_b32 v255, s7, 4
	v_cmp_gt_i64_e64 s[4:5], s[20:21], v[202:203]
	s_nop 1
	v_writelane_b32 v255, s4, 6
	s_and_b64 vcc, exec, s[4:5]
	s_nop 0
	v_writelane_b32 v255, s5, 7
	s_cbranch_vccnz .LBB0_2029
	s_and_b32 s13, s20, 7
	s_lshr_b32 s15, s20, 3
	s_and_b32 s22, s15, 7
	s_lshl_b32 s13, s13, 3
	s_add_u32 s13, s13, s22
	s_lshr_b32 s15, s15, 3
	s_sub_u32 s22, s20, 0x580
	s_and_b32 s23, s22, 3
	s_add_u32 s23, s23, 64
	s_lshr_b32 s22, s22, 2
	s_cmp_lt_u32 s20, 0x580
	s_cselect_b32 s13, s13, s23
	s_cselect_b32 s15, s15, s22
	s_mov_b32 s0, s15
	v_writelane_b32 v255, s0, 0
	v_writelane_b32 v255, s1, 1
	s_mov_b32 s4, s13
	v_writelane_b32 v255, s4, 2
	s_nop 1
	v_writelane_b32 v255, s5, 3

.LBB0_4731:
	v_readlane_b32 s0, v252, 22
	v_readlane_b32 s1, v252, 23
	s_cmp_lt_i32 s0, 19
	s_cselect_b64 s[8:9], -1, 0
	s_cmp_gt_i32 s1, 18
	s_cselect_b64 s[0:1], -1, 0
	s_and_b64 s[0:1], s[8:9], s[0:1]
	s_andn2_b64 vcc, exec, s[0:1]
	s_cbranch_vccnz .LBB0_5010
	s_load_dword s2, s[78:79], 0x2b0
	v_readfirstlane_b32 s10, v248
	s_waitcnt lgkmcnt(0)
	v_cvt_f32_u32_e32 v1, s2
	s_sub_i32 s0, 0, s2
	v_writelane_b32 v254, s2, 56
	v_rcp_iflag_f32_e32 v1, v1
	s_nop 0
	v_mul_f32_e32 v1, 0x4f7ffffe, v1
	v_cvt_u32_f32_e32 v1, v1
	s_nop 0
	v_readfirstlane_b32 s1, v1
	s_mul_i32 s0, s0, s1
	s_mul_hi_u32 s0, s1, s0
	s_add_i32 s1, s1, s0
	s_mul_hi_u32 s0, s76, s1
	s_mul_i32 s0, s0, s2
	s_sub_i32 s0, s76, s0
	s_sub_i32 s1, s0, s2
	s_cmp_ge_u32 s0, s2
	s_cselect_b32 s0, s1, s0
	s_sub_i32 s1, s0, s2
	s_cmp_ge_u32 s0, s2
	s_cselect_b32 s0, s1, s0
	s_cmpk_lt_i32 s0, 0x5d8
	s_cselect_b64 s[2:3], -1, 0
	v_writelane_b32 v254, s0, 46
	s_cmpk_gt_i32 s0, 0x5d7
	s_cbranch_scc1 .LBB0_4734
	v_readlane_b32 s4, v254, 46
	s_and_b32 s12, s4, 7
	s_lshr_b32 s14, s4, 3
	s_and_b32 s0, s14, 7
	s_lshl_b32 s12, s12, 3
	s_add_u32 s12, s12, s0
	s_lshr_b32 s14, s14, 3
	s_sub_u32 s0, s4, 0x580
	s_and_b32 s1, s0, 3
	s_add_u32 s1, s1, 64
	s_lshr_b32 s0, s0, 2
	s_cmp_lt_u32 s4, 0x580
	s_cselect_b32 s12, s12, s1
	s_cselect_b32 s14, s14, s0

.LBB0_4740:
	v_readlane_b32 s5, v254, 48
	s_add_i32 s5, s5, 1
	v_readlane_b32 s4, v252, 18
	s_mul_i32 s10, s5, s4
	v_readlane_b32 s4, v254, 56
	s_mul_hi_u32 s11, s5, s4
	v_writelane_b32 v254, s5, 48
	s_add_i32 s11, s11, s10
	s_mul_i32 s10, s5, s4
	v_readlane_b32 s4, v254, 46
	s_add_u32 s20, s10, s4
	v_readlane_b32 s4, v254, 42
	s_addc_u32 s21, s11, s4
	v_cmp_gt_i64_e64 s[4:5], s[20:21], v[202:203]
	s_nop 1
	v_writelane_b32 v255, s4, 8
	s_and_b64 vcc, exec, s[4:5]
	s_nop 0
	v_writelane_b32 v255, s5, 9
	s_cbranch_vccnz .LBB0_4742
	s_and_b32 s13, s20, 7
	s_lshr_b32 s10, s20, 3
	s_and_b32 s15, s10, 7
	s_lshl_b32 s13, s13, 3
	s_add_u32 s13, s13, s15
	s_lshr_b32 s10, s10, 3
	s_sub_u32 s15, s20, 0x580
	s_and_b32 s22, s15, 3
	s_add_u32 s22, s22, 64
	s_lshr_b32 s15, s15, 2
	s_cmp_lt_u32 s20, 0x580
	s_cselect_b32 s13, s13, s22
	s_cselect_b32 s10, s10, s15
	s_mov_b32 s4, s10
	v_writelane_b32 v252, s4, 58
	s_nop 0
	v_writelane_b32 v252, s5, 59
	s_mov_b32 s4, s13
	v_writelane_b32 v255, s4, 2
	s_nop 1
	v_writelane_b32 v255, s5, 3
